# small per-head GEMMs (phase 7 absorbed queries, phase 9 sample out-proj): heads run concurrently on separate waves spread over all CUs instead of one after another on the first waves
# speedup vs baseline: 1.0467x; 1.0467x over previous
; #define MFMA32(a, b, c) __builtin_amdgcn_mfma_f32_32x32x16_bf16((a), (b), (c), 0, 0, 0)
; template <class Epi> DI void gemm_simple(const bf16_t* A, int lda, const bf16_t* Bt, int ldb, int Mg, int Ng, int K, const Epi& epi, int gw, int ngw, int lane) {
;     const int TN = Ng / 64, TM = Mg / 64, lr = lane & 31, hi = lane >> 5;
;     for (int idx = gw; idx < TM * TN; idx += ngw) {
;         const int tm = idx / TN, tn = idx % TN, m0 = tm * 64, n0 = tn * 64;
;         f32x16 acc[2][2];
; #pragma unroll
;         for (int a = 0; a < 2; ++a)
; #pragma unroll
;             for (int b = 0; b < 2; ++b)
; #pragma unroll
;                 for (int i = 0; i < 16; ++i) acc[a][b][i] = 0.f;
;         const bf16_t* ap = A + (size_t)(m0 + lr) * lda + 8 * hi;
;         const bf16_t* bp = Bt + (size_t)(n0 + lr) * ldb + 8 * hi;
;         const size_t a32 = (size_t)32 * lda, b32 = (size_t)32 * ldb;
; #pragma unroll 4
;         for (int k = 0; k < K; k += 16) {
;             const bf16x8 a0 = *(const bf16x8*)(ap + k), a1 = *(const bf16x8*)(ap + a32 + k);
;             const bf16x8 b0 = *(const bf16x8*)(bp + k), b1 = *(const bf16x8*)(bp + b32 + k);
;             acc[0][0] = MFMA32(b0, a0, acc[0][0]); acc[0][1] = MFMA32(b1, a0, acc[0][1]);
;             acc[1][0] = MFMA32(b0, a1, acc[1][0]); acc[1][1] = MFMA32(b1, a1, acc[1][1]);
;         }
;         epi(acc, m0, n0, lr, hi);
;     }
; }
; DI void run_phase(const Prm& p, int ph, unsigned char* lds, int tid, int wid, int lane) {
;     ...
;         for (int h = 0; h < 4; ++h)
;             gemm_simple((const bf16_t*)(ws + W_Q) + (size_t)ROW_S * 768 + h * 192, 768, (const bf16_t*)(ws + W_WUKV) + h * 256, 1024, 2048, 256, 128, EpiBf{(bf16_t*)(ws + W_QS) + h * 256, 1024}, gw, ngw, lane);
.LBB0_1722:
	s_or_b64 exec, exec, s[0:1]
	s_ashr_i32 s12, s2, 6
	v_readlane_b32 s0, v247, 43
	s_lshl_b32 s12, s12, 8
	s_add_i32 s12, s12, s3
	s_add_u32 s2, s34, 0x1dac3800
	s_addc_u32 s33, s35, 0
	s_cmpk_lt_i32 s12, 0x200
	v_bfe_u32 v1, v14, 5, 1
	s_cselect_b64 s[4:5], -1, 0
	v_lshlrev_b32_e32 v0, 2, v1
	v_mov_b32_e32 v65, 0
	v_lshlrev_b32_e32 v64, 4, v1
	v_cndmask_b32_e64 v1, 0, 1, s[4:5]
	v_and_b32_e32 v78, 31, v14
	v_lshl_add_u64 v[66:67], s[34:35], 0, v[64:65]
	s_lshr_b32 s13, s12, 7
	s_mul_i32 s0, s13, 0x180
	s_mov_b32 s1, 0
	v_cmp_ne_u32_e64 s[4:5], 1, v1
	s_movk_i32 s14, 0x600
	s_mov_b32 s15, 0x15e3a000
	s_mov_b32 s16, 0x15e46000
	s_mov_b32 s17, 0x11d3a000
	s_mov_b32 s18, 0x11d4a000
	s_mov_b64 s[6:7], 0x80
	v_lshlrev_b32_e32 v64, 1, v0
	s_lshl_b32 s8, s13, 9
	s_mov_b32 s9, 0
	s_branch .LBB0_1724
.LBB0_1723:
	s_add_i32 s13, s13, 1
	s_add_u32 s8, s8, 0x200
	s_addc_u32 s9, s9, 0
	s_add_u32 s0, s0, 0x180
	s_addc_u32 s1, s1, 0
	s_nop 0
	s_branch .LBB0_1729
.LBB0_1724:
	s_and_b64 vcc, exec, s[4:5]
	s_cbranch_vccnz .LBB0_1723
	s_lshl_b32 s10, s13, 9
	s_add_u32 s10, s2, s10
	s_addc_u32 s11, s33, 0
	v_mov_b64_e32 v[68:69], s[0:1]
	s_and_b32 s19, s12, 0x7f

; #define MFMA32(a, b, c) __builtin_amdgcn_mfma_f32_32x32x16_bf16((a), (b), (c), 0, 0, 0)
; template <class Epi> DI void gemm_simple(const bf16_t* A, int lda, const bf16_t* Bt, int ldb, int Mg, int Ng, int K, const Epi& epi, int gw, int ngw, int lane) {
;     const int TN = Ng / 64, TM = Mg / 64, lr = lane & 31, hi = lane >> 5;
;     for (int idx = gw; idx < TM * TN; idx += ngw) {
;         const int tm = idx / TN, tn = idx % TN, m0 = tm * 64, n0 = tn * 64;
;         f32x16 acc[2][2];
; #pragma unroll
;         for (int a = 0; a < 2; ++a)
; #pragma unroll
;             for (int b = 0; b < 2; ++b)
; #pragma unroll
;                 for (int i = 0; i < 16; ++i) acc[a][b][i] = 0.f;
;         const bf16_t* ap = A + (size_t)(m0 + lr) * lda + 8 * hi;
;         const bf16_t* bp = Bt + (size_t)(n0 + lr) * ldb + 8 * hi;
;         const size_t a32 = (size_t)32 * lda, b32 = (size_t)32 * ldb;
; #pragma unroll 4
;         for (int k = 0; k < K; k += 16) {
;             const bf16x8 a0 = *(const bf16x8*)(ap + k), a1 = *(const bf16x8*)(ap + a32 + k);
;             const bf16x8 b0 = *(const bf16x8*)(bp + k), b1 = *(const bf16x8*)(bp + b32 + k);
;             acc[0][0] = MFMA32(b0, a0, acc[0][0]); acc[0][1] = MFMA32(b1, a0, acc[0][1]);
;             acc[1][0] = MFMA32(b0, a1, acc[1][0]); acc[1][1] = MFMA32(b1, a1, acc[1][1]);
;         }
;         epi(acc, m0, n0, lr, hi);
;     }
; }
; DI void run_phase(const Prm& p, int ph, unsigned char* lds, int tid, int wid, int lane) {
;     ...
;         for (int h = 0; h < 4; ++h)
;             gemm_simple((const bf16_t*)(ws + W_OL) + h * 256, 1024, (const bf16_t*)(ws + W_WVT) + (size_t)h * 128 * 256, 256, 2048, 128, 256, EpiBf{XN + (size_t)ROW_S * D + 512 + h * 128, D}, gw, ngw, lane);
.LBB0_2043:
	s_and_b32 s0, s0, 7
	s_lshl_b32 s0, s0, 8
	s_add_i32 s0, s0, s3
	s_add_u32 s1, s34, 0x434ac00
	s_addc_u32 s2, s35, 0
	s_cmp_lt_i32 s0, 0x100
	v_lshrrev_b32_e32 v0, 3, v7
	v_lshrrev_b32_e32 v1, 1, v6
	s_cselect_b64 s[4:5], -1, 0
	v_and_b32_e32 v0, 4, v0
	s_waitcnt vmcnt(11)
	v_mov_b32_e32 v65, 0
	v_and_b32_e32 v64, 16, v1
	v_cndmask_b32_e64 v1, 0, 1, s[4:5]
	s_waitcnt vmcnt(8)
	v_and_b32_e32 v76, 31, v6
	v_lshl_add_u64 v[66:67], s[34:35], 0, v[64:65]
	s_lshr_b32 s14, s0, 6
	s_lshl_b32 s6, s14, 9
	s_mov_b32 s7, 0
	v_cmp_ne_u32_e64 s[4:5], 1, v1
	s_mov_b32 s15, 0x1dec3000
	s_mov_b32 s16, 0x1ded3000
	s_mov_b32 s17, 0x11cfa000
	s_mov_b32 s18, 0x11cfe000
	s_mov_b64 s[8:9], 0x80
	v_lshlrev_b32_e32 v64, 1, v0
	s_lshl_b32 s10, s14, 16
	s_mov_b32 s11, 0
	s_branch .LBB0_2045
.LBB0_2044:
	s_add_i32 s14, s14, 1
	s_add_u32 s10, s10, 0x10000
	s_addc_u32 s11, s11, 0
	s_add_u32 s6, s6, 0x200
	s_addc_u32 s7, s7, 0
	s_nop 0
	s_branch .LBB0_2050
.LBB0_2045:
	s_and_b64 vcc, exec, s[4:5]
	s_cbranch_vccnz .LBB0_2044
	s_lshl_b32 s12, s14, 8
	s_add_u32 s12, s1, s12
	s_addc_u32 s13, s2, 0
	s_and_b32 s19, s0, 63
